# job1 (prompt MLA): softmax reference folded into the QK accumulator init (C = -ref block), 64 per-element subtracts per iteration removed
# speedup vs baseline: 1.0069x; 1.0017x over previous
.LBB0_1156:
	s_or_b64 exec, exec, s[62:63]
	v_mul_lo_u32 v34, v32, s52
	v_add_u32_e32 v34, 0, v34
	v_lshlrev_b32_e32 v32, 6, v32
	v_sub_u32_e32 v32, v34, v32
	v_add_u32_e32 v121, v34, v26
	v_add_u32_e32 v122, v32, v26
	s_waitcnt vmcnt(3)
	ds_write_b128 v121, v[82:85]
	s_waitcnt vmcnt(2)
	ds_write_b128 v122, v[86:89] offset:13312
	s_and_saveexec_b64 s[42:43], s[8:9]
	s_xor_b64 s[8:9], exec, s[42:43]
	v_lshlrev_b32_e32 v123, 4, v33
	s_or_saveexec_b64 s[8:9], s[8:9]
	v_mul_u32_u24_e32 v27, 0xd0, v27
	s_xor_b64 exec, exec, s[8:9]
	v_add3_u32 v32, 0, v27, v30
	v_mov_b32_e32 v123, v30
	ds_write_b128 v32, v[90:93] offset:128
	s_or_b64 exec, exec, s[8:9]
	v_lshrrev_b32_e32 v32, 2, v31
	v_mad_u32_u24 v124, v1, s52, 0
	v_lshlrev_b32_e32 v1, 2, v38
	v_and_or_b32 v32, v32, 3, v1
	v_mad_u32_u24 v125, v32, s82, 0
	v_and_b32_e32 v32, 16, v31
	v_lshlrev_b32_e32 v33, 2, v31
	v_and_or_b32 v32, v33, 12, v32
	v_lshlrev_b32_e32 v34, 16, v6
	v_and_b32_e32 v35, 0xffff0000, v6
	v_mov_b32_e32 v37, v24
	v_mov_b32_e32 v24, v23
	v_lshlrev_b32_e32 v126, 1, v32
	v_lshlrev_b32_e32 v32, 16, v10
	v_and_b32_e32 v33, 0xffff0000, v10
	v_mov_b32_e32 v36, v22
	v_pk_mul_f32 v[22:23], v[24:25], v[34:35]
	v_lshlrev_b32_e32 v6, 16, v7
	v_pk_fma_f32 v[22:23], v[36:37], v[32:33], v[22:23] neg_lo:[0,0,1] neg_hi:[0,0,1]
	v_and_b32_e32 v7, 0xffff0000, v7
	v_cvt_pk_bf16_f32 v106, v22, v23
	v_pk_mul_f32 v[22:23], v[36:37], v[34:35]
	v_lshlrev_b32_e32 v10, 16, v11
	v_pk_fma_f32 v[22:23], v[24:25], v[32:33], v[22:23]
	v_and_b32_e32 v11, 0xffff0000, v11
	v_cvt_pk_bf16_f32 v110, v22, v23
	v_mov_b32_e32 v23, v20
	v_mov_b32_e32 v20, v19
	v_mov_b32_e32 v22, v18
	v_pk_mul_f32 v[18:19], v[20:21], v[6:7]
	v_pk_mul_f32 v[6:7], v[22:23], v[6:7]
	v_pk_fma_f32 v[18:19], v[22:23], v[10:11], v[18:19] neg_lo:[0,0,1] neg_hi:[0,0,1]
	v_pk_fma_f32 v[6:7], v[20:21], v[10:11], v[6:7]
	v_cvt_pk_bf16_f32 v107, v18, v19
	v_lshlrev_b32_e32 v10, 16, v8
	v_and_b32_e32 v11, 0xffff0000, v8
	v_mov_b32_e32 v18, v14
	v_mov_b32_e32 v19, v16
	v_mov_b32_e32 v16, v15
	v_cvt_pk_bf16_f32 v111, v6, v7
	v_lshlrev_b32_e32 v6, 16, v12
	v_and_b32_e32 v7, 0xffff0000, v12
	v_pk_mul_f32 v[14:15], v[16:17], v[10:11]
	v_pk_mul_f32 v[10:11], v[18:19], v[10:11]
	v_pk_fma_f32 v[14:15], v[18:19], v[6:7], v[14:15] neg_lo:[0,0,1] neg_hi:[0,0,1]
	v_pk_fma_f32 v[6:7], v[16:17], v[6:7], v[10:11]
	v_lshlrev_b32_e32 v8, 16, v9
	v_and_b32_e32 v9, 0xffff0000, v9
	v_mov_b32_e32 v11, v4
	v_mov_b32_e32 v4, v3
	v_cvt_pk_bf16_f32 v112, v6, v7
	v_lshlrev_b32_e32 v6, 16, v13
	v_and_b32_e32 v7, 0xffff0000, v13
	v_mov_b32_e32 v10, v2
	v_pk_mul_f32 v[2:3], v[4:5], v[8:9]
	s_addk_i32 s66, 0x100
	v_pk_fma_f32 v[2:3], v[10:11], v[6:7], v[2:3] neg_lo:[0,0,1] neg_hi:[0,0,1]
	v_add_u32_e32 v127, 0, v27
	v_cvt_pk_bf16_f32 v109, v2, v3
	v_pk_mul_f32 v[2:3], v[10:11], v[8:9]
	v_mov_b32_e32 v27, v199
	v_pk_fma_f32 v[2:3], v[4:5], v[6:7], v[2:3]
	v_mov_b32_e32 v16, v199
	v_cvt_pk_bf16_f32 v113, v2, v3
	v_lshlrev_b32_e32 v2, 4, v31
	v_and_b32_e32 v2, 0xfc0, v2
	v_mov_b32_e32 v3, v199
	v_lshl_add_u64 v[2:3], s[36:37], 0, v[2:3]
	v_mov_b32_e32 v31, v199
	v_lshl_add_u64 v[116:117], v[2:3], 0, v[30:31]
	v_lshl_add_u64 v[2:3], s[12:13], 0, v[28:29]
	v_mov_b32_e32 v17, v199
	v_cvt_pk_bf16_f32 v108, v14, v15
	s_lshr_b32 s67, s66, 6
	v_lshl_add_u64 v[118:119], v[2:3], 0, v[26:27]
	v_mov_b32_e32 v2, v199
	v_mov_b32_e32 v3, v199
	v_mov_b32_e32 v4, v199
	v_mov_b32_e32 v5, v199
	v_mov_b32_e32 v6, v199
	v_mov_b32_e32 v7, v199
	v_mov_b32_e32 v8, v199
	v_mov_b32_e32 v9, v199
	v_mov_b32_e32 v10, v199
	v_mov_b32_e32 v11, v199
	v_mov_b32_e32 v12, v199
	v_mov_b32_e32 v13, v199
	v_mov_b32_e32 v14, v199
	v_mov_b32_e32 v15, v199
	v_mov_b64_e32 v[32:33], v[16:17]
	s_xor_b64 s[8:9], s[60:61], -1
	s_mov_b32 s47, s11
	v_ashrrev_i32_e32 v115, 31, v114
	s_add_i32 s38, s67, -2
	s_ashr_i32 s39, s39, 6
	s_mov_b32 s44, 0
	v_mov_b32_e32 v129, 0xf149f2ca
	v_mov_b32_e32 v236, 0xf149f2ca
	v_mov_b32_e32 v220, v199
	v_mov_b32_e32 v221, v199
	v_mov_b32_e32 v222, v199
	v_mov_b32_e32 v223, v199
	v_mov_b32_e32 v224, v199
	v_mov_b32_e32 v225, v199
	v_mov_b32_e32 v226, v199
	v_mov_b32_e32 v227, v199
	v_mov_b32_e32 v228, v199
	v_mov_b32_e32 v229, v199
	v_mov_b32_e32 v230, v199
	v_mov_b32_e32 v231, v199
	v_mov_b32_e32 v232, v199
	v_mov_b32_e32 v233, v199
	v_mov_b32_e32 v234, v199
	v_mov_b32_e32 v235, v199
	v_mov_b32_e32 v128, 0
	s_mov_b32 s42, 64
	v_mov_b64_e32 v[30:31], v[14:15]
	v_mov_b64_e32 v[28:29], v[12:13]
	v_mov_b64_e32 v[26:27], v[10:11]
	v_mov_b64_e32 v[24:25], v[8:9]
	v_mov_b64_e32 v[22:23], v[6:7]
	v_mov_b64_e32 v[20:21], v[4:5]
	v_mov_b64_e32 v[18:19], v[2:3]
	s_waitcnt lgkmcnt(0)
	s_barrier

.LBB0_1165:
	s_sub_i32 s45, s42, 64
	s_cmp_ge_u32 s45, s66
	s_cselect_b64 s[48:49], -1, 0
	s_cmp_gt_i32 s44, s39
	s_cselect_b64 s[50:51], -1, 0
	s_or_b64 s[48:49], s[50:51], s[48:49]
	s_and_b64 vcc, exec, s[48:49]
	s_cbranch_vccnz .LBB0_1169
	v_add_u32_e32 v120, v124, v198
	ds_read_b128 v[136:139], v120
	ds_read_b128 v[140:143], v120 offset:6656
	ds_read_b128 v[144:147], v120 offset:32
	ds_read_b128 v[148:151], v120 offset:6688
	ds_read_b128 v[152:155], v120 offset:64
	ds_read_b128 v[156:159], v120 offset:6720
	ds_read_b128 v[160:163], v120 offset:96
	ds_read_b128 v[164:167], v120 offset:6752
	ds_read_b128 v[168:171], v120 offset:128
	ds_read_b128 v[172:175], v120 offset:6784
	ds_read_b128 v[176:179], v120 offset:160
	ds_read_b128 v[180:183], v120 offset:6816
	v_add_u32_e32 v184, v125, v126
	s_waitcnt lgkmcnt(11)
	v_mfma_f32_32x32x16_bf16 v[34:49], v[136:139], v[66:69], v[220:235]
	s_waitcnt lgkmcnt(10)
	v_mfma_f32_32x32x16_bf16 v[50:65], v[140:143], v[66:69], v[220:235]
	s_waitcnt lgkmcnt(9)
	v_mfma_f32_32x32x16_bf16 v[34:49], v[144:147], v[70:73], v[34:49]
	s_waitcnt lgkmcnt(8)
	v_mfma_f32_32x32x16_bf16 v[50:65], v[148:151], v[70:73], v[50:65]
	s_waitcnt lgkmcnt(7)
	v_mfma_f32_32x32x16_bf16 v[34:49], v[152:155], v[74:77], v[34:49]
	s_waitcnt lgkmcnt(6)
	v_mfma_f32_32x32x16_bf16 v[50:65], v[156:159], v[74:77], v[50:65]
	s_waitcnt lgkmcnt(5)
	v_mfma_f32_32x32x16_bf16 v[34:49], v[160:163], v[78:81], v[34:49]
	s_waitcnt lgkmcnt(4)
	v_mfma_f32_32x32x16_bf16 v[50:65], v[164:167], v[78:81], v[50:65]
	s_waitcnt lgkmcnt(3)
	v_mfma_f32_32x32x16_bf16 v[34:49], v[168:171], v[106:109], v[34:49]
	s_waitcnt lgkmcnt(2)
	v_mfma_f32_32x32x16_bf16 v[50:65], v[172:175], v[106:109], v[50:65]
	s_waitcnt lgkmcnt(1)
	v_mfma_f32_32x32x16_bf16 v[34:49], v[176:179], v[110:113], v[34:49]
	s_waitcnt lgkmcnt(0)
	v_mfma_f32_32x32x16_bf16 v[50:65], v[180:183], v[110:113], v[50:65]
	s_nop 11
	v_max3_f32 v120, v34, v35, v36
	v_max3_f32 v120, v120, v37, v38
	v_max3_f32 v120, v120, v39, v40
	v_max3_f32 v120, v120, v41, v42
	v_max3_f32 v120, v120, v43, v44
	v_max3_f32 v120, v120, v45, v46
	v_max3_f32 v120, v120, v47, v48
	v_max3_f32 v120, v120, v49, v50
	v_max3_f32 v120, v120, v51, v52
	v_max3_f32 v120, v120, v53, v54
	v_max3_f32 v120, v120, v55, v56
	v_max3_f32 v120, v120, v57, v58
	v_max3_f32 v120, v120, v59, v60
	v_max3_f32 v120, v120, v61, v62
	v_max3_f32 v120, v120, v63, v64
	v_max_f32_e32 v120, v120, v65
	v_sub_f32_e32 v130, v236, v120
	v_cmp_gt_f32_e32 vcc, 0xc2200000, v130
	s_cbranch_vccnz .Llazy8_full
	ds_read_b64_tr_b16 v[136:137], v184 offset:13312
	ds_read_b64_tr_b16 v[138:139], v184 offset:14464
	ds_read_b64_tr_b16 v[140:141], v184 offset:13376
	ds_read_b64_tr_b16 v[142:143], v184 offset:14528
	ds_read_b64_tr_b16 v[144:145], v184 offset:15616
	ds_read_b64_tr_b16 v[146:147], v184 offset:16768
	ds_read_b64_tr_b16 v[148:149], v184 offset:15680
	ds_read_b64_tr_b16 v[150:151], v184 offset:16832
	ds_read_b64_tr_b16 v[152:153], v184 offset:17920
	ds_read_b64_tr_b16 v[154:155], v184 offset:19072
	ds_read_b64_tr_b16 v[156:157], v184 offset:17984
	ds_read_b64_tr_b16 v[158:159], v184 offset:19136
	ds_read_b64_tr_b16 v[160:161], v184 offset:20224
	ds_read_b64_tr_b16 v[162:163], v184 offset:21376
	ds_read_b64_tr_b16 v[164:165], v184 offset:20288
	ds_read_b64_tr_b16 v[166:167], v184 offset:21440
	v_mov_b32_e32 v130, v129
	v_mov_b32_e32 v120, 1.0
	s_branch .LBB0_1168
.Llazy8_full:
	v_and_b32_e32 v131, 64, v218
	v_xor_b32_e32 v130, 32, v218
	v_add_u32_e32 v131, 64, v131
	v_cmp_lt_i32_e32 vcc, v130, v131
	s_nop 1
	v_cndmask_b32_e32 v130, v218, v130, vcc
	v_lshlrev_b32_e32 v130, 2, v130
	ds_bpermute_b32 v130, v130, v120
	s_waitcnt lgkmcnt(0)
	ds_read_b64_tr_b16 v[136:137], v184 offset:13312
	ds_read_b64_tr_b16 v[138:139], v184 offset:14464
	ds_read_b64_tr_b16 v[140:141], v184 offset:13376
	ds_read_b64_tr_b16 v[142:143], v184 offset:14528
	ds_read_b64_tr_b16 v[144:145], v184 offset:15616
	ds_read_b64_tr_b16 v[146:147], v184 offset:16768
	ds_read_b64_tr_b16 v[148:149], v184 offset:15680
	ds_read_b64_tr_b16 v[150:151], v184 offset:16832
	ds_read_b64_tr_b16 v[152:153], v184 offset:17920
	ds_read_b64_tr_b16 v[154:155], v184 offset:19072
	ds_read_b64_tr_b16 v[156:157], v184 offset:17984
	ds_read_b64_tr_b16 v[158:159], v184 offset:19136
	ds_read_b64_tr_b16 v[160:161], v184 offset:20224
	ds_read_b64_tr_b16 v[162:163], v184 offset:21376
	ds_read_b64_tr_b16 v[164:165], v184 offset:20288
	ds_read_b64_tr_b16 v[166:167], v184 offset:21440
	v_max_f32_e32 v130, v120, v130
	v_max_f32_e32 v130, v130, v236
	v_max_f32_e32 v120, 0, v130
	v_exp_f32_e64 v120, -v120
	v_mov_b32_e32 v236, 0
	v_sub_f32_e32 v34, v34, v130
	v_sub_f32_e32 v35, v35, v130
	v_sub_f32_e32 v36, v36, v130
	v_sub_f32_e32 v37, v37, v130
	v_sub_f32_e32 v38, v38, v130
	v_sub_f32_e32 v39, v39, v130
	v_sub_f32_e32 v40, v40, v130
	v_sub_f32_e32 v41, v41, v130
	v_sub_f32_e32 v42, v42, v130
	v_sub_f32_e32 v43, v43, v130
	v_sub_f32_e32 v44, v44, v130
	v_sub_f32_e32 v45, v45, v130
	v_sub_f32_e32 v46, v46, v130
	v_sub_f32_e32 v47, v47, v130
	v_sub_f32_e32 v48, v48, v130
	v_sub_f32_e32 v49, v49, v130
	v_sub_f32_e32 v50, v50, v130
	v_sub_f32_e32 v51, v51, v130
	v_sub_f32_e32 v52, v52, v130
	v_sub_f32_e32 v53, v53, v130
	v_sub_f32_e32 v54, v54, v130
	v_sub_f32_e32 v55, v55, v130
	v_sub_f32_e32 v56, v56, v130
	v_sub_f32_e32 v57, v57, v130
	v_sub_f32_e32 v58, v58, v130
	v_sub_f32_e32 v59, v59, v130
	v_sub_f32_e32 v60, v60, v130
	v_sub_f32_e32 v61, v61, v130
	v_sub_f32_e32 v62, v62, v130
	v_sub_f32_e32 v63, v63, v130
	v_sub_f32_e32 v64, v64, v130
	v_sub_f32_e32 v65, v65, v130
	v_sub_f32_e32 v220, v220, v130
	v_sub_f32_e32 v221, v221, v130
	v_sub_f32_e32 v222, v222, v130
	v_sub_f32_e32 v223, v223, v130
	v_sub_f32_e32 v224, v224, v130
	v_sub_f32_e32 v225, v225, v130
	v_sub_f32_e32 v226, v226, v130
	v_sub_f32_e32 v227, v227, v130
	v_sub_f32_e32 v228, v228, v130
	v_sub_f32_e32 v229, v229, v130
	v_sub_f32_e32 v230, v230, v130
	v_sub_f32_e32 v231, v231, v130
	v_sub_f32_e32 v232, v232, v130
	v_sub_f32_e32 v233, v233, v130
	v_sub_f32_e32 v234, v234, v130
	v_sub_f32_e32 v235, v235, v130
	v_cmp_neq_f32_e32 vcc, 1.0, v120
	s_cbranch_vccz .LBB0_1168
	v_pk_mul_f32 v[16:17], v[16:17], v[120:121] op_sel_hi:[1,0]
	v_pk_mul_f32 v[14:15], v[14:15], v[120:121] op_sel_hi:[1,0]
	v_pk_mul_f32 v[12:13], v[12:13], v[120:121] op_sel_hi:[1,0]
	v_pk_mul_f32 v[10:11], v[10:11], v[120:121] op_sel_hi:[1,0]
	v_pk_mul_f32 v[8:9], v[8:9], v[120:121] op_sel_hi:[1,0]
	v_pk_mul_f32 v[6:7], v[6:7], v[120:121] op_sel_hi:[1,0]
	v_pk_mul_f32 v[4:5], v[4:5], v[120:121] op_sel_hi:[1,0]
	v_pk_mul_f32 v[2:3], v[2:3], v[120:121] op_sel_hi:[1,0]
	v_pk_mul_f32 v[32:33], v[32:33], v[120:121] op_sel_hi:[1,0]
	v_pk_mul_f32 v[30:31], v[30:31], v[120:121] op_sel_hi:[1,0]
	v_pk_mul_f32 v[28:29], v[28:29], v[120:121] op_sel_hi:[1,0]
	v_pk_mul_f32 v[26:27], v[26:27], v[120:121] op_sel_hi:[1,0]
	v_pk_mul_f32 v[24:25], v[24:25], v[120:121] op_sel_hi:[1,0]
	v_pk_mul_f32 v[22:23], v[22:23], v[120:121] op_sel_hi:[1,0]
	v_pk_mul_f32 v[20:21], v[20:21], v[120:121] op_sel_hi:[1,0]
	v_pk_mul_f32 v[18:19], v[18:19], v[120:121] op_sel_hi:[1,0]
.LBB0_1168:
	v_exp_f32_e32 v34, v34
	v_exp_f32_e32 v50, v50
	v_exp_f32_e32 v35, v35
	v_exp_f32_e32 v51, v51
	v_exp_f32_e32 v36, v36
	v_exp_f32_e32 v52, v52
	v_exp_f32_e32 v37, v37
	v_exp_f32_e32 v53, v53
	v_add_f32_e32 v129, v34, v50
	v_exp_f32_e32 v38, v38
	v_exp_f32_e32 v54, v54
	v_add_f32_e32 v129, 0, v129
	v_add_f32_e32 v131, v35, v51
	v_exp_f32_e32 v39, v39
	v_exp_f32_e32 v55, v55
	v_add_f32_e32 v129, v131, v129
	v_add_f32_e32 v131, v36, v52
	v_exp_f32_e32 v40, v40
	v_exp_f32_e32 v56, v56
	v_add_f32_e32 v129, v131, v129
	v_add_f32_e32 v131, v37, v53
	v_exp_f32_e32 v41, v41
	v_exp_f32_e32 v57, v57
	v_add_f32_e32 v129, v131, v129
	v_add_f32_e32 v131, v38, v54
	v_exp_f32_e32 v42, v42
	v_exp_f32_e32 v58, v58
	v_add_f32_e32 v129, v131, v129
	v_add_f32_e32 v131, v39, v55
	v_exp_f32_e32 v43, v43
	v_exp_f32_e32 v59, v59
	v_add_f32_e32 v129, v131, v129
	v_add_f32_e32 v131, v40, v56
	v_exp_f32_e32 v44, v44
	v_exp_f32_e32 v60, v60
	v_add_f32_e32 v129, v131, v129
	v_add_f32_e32 v131, v41, v57
	v_exp_f32_e32 v45, v45
	v_exp_f32_e32 v61, v61
	v_add_f32_e32 v129, v131, v129
	v_add_f32_e32 v131, v42, v58
	v_add_f32_e32 v129, v131, v129
	v_add_f32_e32 v131, v43, v59
	v_add_f32_e32 v129, v131, v129
	v_add_f32_e32 v131, v44, v60
	v_add_f32_e32 v129, v131, v129
	v_add_f32_e32 v131, v45, v61
	v_add_f32_e32 v129, v131, v129
	v_exp_f32_e32 v131, v46
	v_exp_f32_e32 v62, v62
	v_cvt_pk_bf16_f32 v42, v42, v43
	v_cvt_pk_bf16_f32 v43, v44, v45
	v_add_f32_e32 v46, v131, v62
	v_add_f32_e32 v46, v46, v129
	v_exp_f32_e32 v129, v47
	v_exp_f32_e32 v63, v63
	v_cvt_pk_bf16_f32 v44, v131, v129
	v_add_f32_e32 v47, v129, v63
	v_add_f32_e32 v46, v47, v46
	v_exp_f32_e32 v132, v48
	v_exp_f32_e32 v64, v64
	v_cvt_pk_bf16_f32 v48, v38, v39
	v_cvt_pk_bf16_f32 v38, v50, v51
	v_cvt_pk_bf16_f32 v39, v52, v53
	v_add_f32_e32 v47, v132, v64
	v_add_f32_e32 v46, v47, v46
	v_exp_f32_e32 v133, v49
	v_exp_f32_e32 v65, v65
	v_cvt_pk_bf16_f32 v49, v40, v41
	v_cvt_pk_bf16_f32 v40, v54, v55
	v_cvt_pk_bf16_f32 v41, v56, v57
	v_add_f32_e32 v47, v133, v65
	v_add_f32_e32 v134, v47, v46
	v_cvt_pk_bf16_f32 v46, v34, v35
	v_cvt_pk_bf16_f32 v34, v58, v59
	v_cvt_pk_bf16_f32 v47, v36, v37
	v_cvt_pk_bf16_f32 v45, v132, v133
	v_cvt_pk_bf16_f32 v35, v60, v61
	s_waitcnt lgkmcnt(0)
	v_mfma_f32_32x32x16_bf16 v[2:17], v[136:139], v[46:49], v[2:17]
	v_cvt_pk_bf16_f32 v36, v62, v63
	v_cvt_pk_bf16_f32 v37, v64, v65
	v_fmac_f32_e32 v134, v128, v120
	v_mov_b32_e32 v128, v134
	v_mfma_f32_32x32x16_bf16 v[18:33], v[140:143], v[46:49], v[18:33]
	v_mfma_f32_32x32x16_bf16 v[2:17], v[144:147], v[42:45], v[2:17]
	v_mfma_f32_32x32x16_bf16 v[18:33], v[148:151], v[42:45], v[18:33]
	v_mfma_f32_32x32x16_bf16 v[2:17], v[152:155], v[38:41], v[2:17]
	v_mfma_f32_32x32x16_bf16 v[18:33], v[156:159], v[38:41], v[18:33]
	v_mfma_f32_32x32x16_bf16 v[2:17], v[160:163], v[34:37], v[2:17]
	v_mfma_f32_32x32x16_bf16 v[18:33], v[164:167], v[34:37], v[18:33]
	s_branch .LBB0_1170

.LBB0_1179:
	s_cmp_ge_u32 s42, s66
	s_cselect_b64 s[48:49], -1, 0
	s_cmp_ge_i32 s44, s39
	s_cselect_b64 s[50:51], -1, 0
	s_or_b64 s[48:49], s[50:51], s[48:49]
	s_and_b64 vcc, exec, s[48:49]
	s_cbranch_vccnz .LBB0_1184
	v_add_u32_e32 v120, v124, v198
	ds_read_b128 v[136:139], v120 offset:32768
	ds_read_b128 v[140:143], v120 offset:39424
	ds_read_b128 v[144:147], v120 offset:32800
	ds_read_b128 v[148:151], v120 offset:39456
	ds_read_b128 v[152:155], v120 offset:32832
	ds_read_b128 v[156:159], v120 offset:39488
	ds_read_b128 v[160:163], v120 offset:32864
	ds_read_b128 v[164:167], v120 offset:39520
	ds_read_b128 v[168:171], v120 offset:32896
	ds_read_b128 v[172:175], v120 offset:39552
	ds_read_b128 v[176:179], v120 offset:32928
	ds_read_b128 v[180:183], v120 offset:39584
	v_add_u32_e32 v184, v125, v126
	s_waitcnt lgkmcnt(11)
	v_mfma_f32_32x32x16_bf16 v[34:49], v[136:139], v[66:69], v[220:235]
	s_waitcnt lgkmcnt(10)
	v_mfma_f32_32x32x16_bf16 v[50:65], v[140:143], v[66:69], v[220:235]
	s_waitcnt lgkmcnt(9)
	v_mfma_f32_32x32x16_bf16 v[34:49], v[144:147], v[70:73], v[34:49]
	s_waitcnt lgkmcnt(8)
	v_mfma_f32_32x32x16_bf16 v[50:65], v[148:151], v[70:73], v[50:65]
	s_waitcnt lgkmcnt(7)
	v_mfma_f32_32x32x16_bf16 v[34:49], v[152:155], v[74:77], v[34:49]
	s_waitcnt lgkmcnt(6)
	v_mfma_f32_32x32x16_bf16 v[50:65], v[156:159], v[74:77], v[50:65]
	s_waitcnt lgkmcnt(5)
	v_mfma_f32_32x32x16_bf16 v[34:49], v[160:163], v[78:81], v[34:49]
	s_waitcnt lgkmcnt(4)
	v_mfma_f32_32x32x16_bf16 v[50:65], v[164:167], v[78:81], v[50:65]
	s_waitcnt lgkmcnt(3)
	v_mfma_f32_32x32x16_bf16 v[34:49], v[168:171], v[106:109], v[34:49]
	s_waitcnt lgkmcnt(2)
	v_mfma_f32_32x32x16_bf16 v[50:65], v[172:175], v[106:109], v[50:65]
	s_waitcnt lgkmcnt(1)
	v_mfma_f32_32x32x16_bf16 v[34:49], v[176:179], v[110:113], v[34:49]
	s_waitcnt lgkmcnt(0)
	v_mfma_f32_32x32x16_bf16 v[50:65], v[180:183], v[110:113], v[50:65]
	s_nop 11
	v_max3_f32 v120, v34, v35, v36
	v_max3_f32 v120, v120, v37, v38
	v_max3_f32 v120, v120, v39, v40
	v_max3_f32 v120, v120, v41, v42
	v_max3_f32 v120, v120, v43, v44
	v_max3_f32 v120, v120, v45, v46
	v_max3_f32 v120, v120, v47, v48
	v_max3_f32 v120, v120, v49, v50
	v_max3_f32 v120, v120, v51, v52
	v_max3_f32 v120, v120, v53, v54
	v_max3_f32 v120, v120, v55, v56
	v_max3_f32 v120, v120, v57, v58
	v_max3_f32 v120, v120, v59, v60
	v_max3_f32 v120, v120, v61, v62
	v_max3_f32 v120, v120, v63, v64
	v_max_f32_e32 v120, v120, v65
	v_sub_f32_e32 v129, v236, v120
	v_cmp_gt_f32_e32 vcc, 0xc2200000, v129
	s_cbranch_vccnz .Llazy9_full
	ds_read_b64_tr_b16 v[136:137], v184 offset:46080
	ds_read_b64_tr_b16 v[138:139], v184 offset:47232
	ds_read_b64_tr_b16 v[140:141], v184 offset:46144
	ds_read_b64_tr_b16 v[142:143], v184 offset:47296
	ds_read_b64_tr_b16 v[144:145], v184 offset:48384
	ds_read_b64_tr_b16 v[146:147], v184 offset:49536
	ds_read_b64_tr_b16 v[148:149], v184 offset:48448
	ds_read_b64_tr_b16 v[150:151], v184 offset:49600
	ds_read_b64_tr_b16 v[152:153], v184 offset:50688
	ds_read_b64_tr_b16 v[154:155], v184 offset:51840
	ds_read_b64_tr_b16 v[156:157], v184 offset:50752
	ds_read_b64_tr_b16 v[158:159], v184 offset:51904
	ds_read_b64_tr_b16 v[160:161], v184 offset:52992
	ds_read_b64_tr_b16 v[162:163], v184 offset:54144
	ds_read_b64_tr_b16 v[164:165], v184 offset:53056
	ds_read_b64_tr_b16 v[166:167], v184 offset:54208
	v_mov_b32_e32 v129, v130
	v_mov_b32_e32 v120, 1.0
	s_branch .LBB0_1182
.Llazy9_full:
	v_and_b32_e32 v131, 64, v218
	v_xor_b32_e32 v129, 32, v218
	v_add_u32_e32 v131, 64, v131
	v_cmp_lt_i32_e32 vcc, v129, v131
	s_nop 1
	v_cndmask_b32_e32 v129, v218, v129, vcc
	v_lshlrev_b32_e32 v129, 2, v129
	ds_bpermute_b32 v129, v129, v120
	s_waitcnt lgkmcnt(0)
	ds_read_b64_tr_b16 v[136:137], v184 offset:46080
	ds_read_b64_tr_b16 v[138:139], v184 offset:47232
	ds_read_b64_tr_b16 v[140:141], v184 offset:46144
	ds_read_b64_tr_b16 v[142:143], v184 offset:47296
	ds_read_b64_tr_b16 v[144:145], v184 offset:48384
	ds_read_b64_tr_b16 v[146:147], v184 offset:49536
	ds_read_b64_tr_b16 v[148:149], v184 offset:48448
	ds_read_b64_tr_b16 v[150:151], v184 offset:49600
	ds_read_b64_tr_b16 v[152:153], v184 offset:50688
	ds_read_b64_tr_b16 v[154:155], v184 offset:51840
	ds_read_b64_tr_b16 v[156:157], v184 offset:50752
	ds_read_b64_tr_b16 v[158:159], v184 offset:51904
	ds_read_b64_tr_b16 v[160:161], v184 offset:52992
	ds_read_b64_tr_b16 v[162:163], v184 offset:54144
	ds_read_b64_tr_b16 v[164:165], v184 offset:53056
	ds_read_b64_tr_b16 v[166:167], v184 offset:54208
	v_max_f32_e32 v129, v120, v129
	v_max_f32_e32 v129, v129, v236
	v_max_f32_e32 v120, 0, v129
	v_exp_f32_e64 v120, -v120
	v_mov_b32_e32 v236, 0
	v_sub_f32_e32 v34, v34, v129
	v_sub_f32_e32 v35, v35, v129
	v_sub_f32_e32 v36, v36, v129
	v_sub_f32_e32 v37, v37, v129
	v_sub_f32_e32 v38, v38, v129
	v_sub_f32_e32 v39, v39, v129
	v_sub_f32_e32 v40, v40, v129
	v_sub_f32_e32 v41, v41, v129
	v_sub_f32_e32 v42, v42, v129
	v_sub_f32_e32 v43, v43, v129
	v_sub_f32_e32 v44, v44, v129
	v_sub_f32_e32 v45, v45, v129
	v_sub_f32_e32 v46, v46, v129
	v_sub_f32_e32 v47, v47, v129
	v_sub_f32_e32 v48, v48, v129
	v_sub_f32_e32 v49, v49, v129
	v_sub_f32_e32 v50, v50, v129
	v_sub_f32_e32 v51, v51, v129
	v_sub_f32_e32 v52, v52, v129
	v_sub_f32_e32 v53, v53, v129
	v_sub_f32_e32 v54, v54, v129
	v_sub_f32_e32 v55, v55, v129
	v_sub_f32_e32 v56, v56, v129
	v_sub_f32_e32 v57, v57, v129
	v_sub_f32_e32 v58, v58, v129
	v_sub_f32_e32 v59, v59, v129
	v_sub_f32_e32 v60, v60, v129
	v_sub_f32_e32 v61, v61, v129
	v_sub_f32_e32 v62, v62, v129
	v_sub_f32_e32 v63, v63, v129
	v_sub_f32_e32 v64, v64, v129
	v_sub_f32_e32 v65, v65, v129
	v_sub_f32_e32 v220, v220, v129
	v_sub_f32_e32 v221, v221, v129
	v_sub_f32_e32 v222, v222, v129
	v_sub_f32_e32 v223, v223, v129
	v_sub_f32_e32 v224, v224, v129
	v_sub_f32_e32 v225, v225, v129
	v_sub_f32_e32 v226, v226, v129
	v_sub_f32_e32 v227, v227, v129
	v_sub_f32_e32 v228, v228, v129
	v_sub_f32_e32 v229, v229, v129
	v_sub_f32_e32 v230, v230, v129
	v_sub_f32_e32 v231, v231, v129
	v_sub_f32_e32 v232, v232, v129
	v_sub_f32_e32 v233, v233, v129
	v_sub_f32_e32 v234, v234, v129
	v_sub_f32_e32 v235, v235, v129
	v_cmp_neq_f32_e32 vcc, 1.0, v120
	s_cbranch_vccz .LBB0_1182
	v_pk_mul_f32 v[16:17], v[16:17], v[120:121] op_sel_hi:[1,0]
	v_pk_mul_f32 v[14:15], v[14:15], v[120:121] op_sel_hi:[1,0]
	v_pk_mul_f32 v[12:13], v[12:13], v[120:121] op_sel_hi:[1,0]
	v_pk_mul_f32 v[10:11], v[10:11], v[120:121] op_sel_hi:[1,0]
	v_pk_mul_f32 v[8:9], v[8:9], v[120:121] op_sel_hi:[1,0]
	v_pk_mul_f32 v[6:7], v[6:7], v[120:121] op_sel_hi:[1,0]
	v_pk_mul_f32 v[4:5], v[4:5], v[120:121] op_sel_hi:[1,0]
	v_pk_mul_f32 v[2:3], v[2:3], v[120:121] op_sel_hi:[1,0]
	v_pk_mul_f32 v[32:33], v[32:33], v[120:121] op_sel_hi:[1,0]
	v_pk_mul_f32 v[30:31], v[30:31], v[120:121] op_sel_hi:[1,0]
	v_pk_mul_f32 v[28:29], v[28:29], v[120:121] op_sel_hi:[1,0]
	v_pk_mul_f32 v[26:27], v[26:27], v[120:121] op_sel_hi:[1,0]
	v_pk_mul_f32 v[24:25], v[24:25], v[120:121] op_sel_hi:[1,0]
	v_pk_mul_f32 v[22:23], v[22:23], v[120:121] op_sel_hi:[1,0]
	v_pk_mul_f32 v[20:21], v[20:21], v[120:121] op_sel_hi:[1,0]
	v_pk_mul_f32 v[18:19], v[18:19], v[120:121] op_sel_hi:[1,0]
.LBB0_1182:
	v_exp_f32_e32 v34, v34
	v_exp_f32_e32 v50, v50
	v_exp_f32_e32 v35, v35
	v_exp_f32_e32 v51, v51
	v_exp_f32_e32 v36, v36
	v_exp_f32_e32 v52, v52
	v_exp_f32_e32 v37, v37
	v_exp_f32_e32 v53, v53
	v_add_f32_e32 v130, v34, v50
	v_exp_f32_e32 v38, v38
	v_exp_f32_e32 v54, v54
	v_add_f32_e32 v130, 0, v130
	v_add_f32_e32 v131, v35, v51
	v_exp_f32_e32 v39, v39
	v_exp_f32_e32 v55, v55
	v_add_f32_e32 v130, v131, v130
	v_add_f32_e32 v131, v36, v52
	v_exp_f32_e32 v40, v40
	v_exp_f32_e32 v56, v56
	v_add_f32_e32 v130, v131, v130
	v_add_f32_e32 v131, v37, v53
	v_exp_f32_e32 v41, v41
	v_exp_f32_e32 v57, v57
	v_add_f32_e32 v130, v131, v130
	v_add_f32_e32 v131, v38, v54
	v_exp_f32_e32 v42, v42
	v_exp_f32_e32 v58, v58
	v_add_f32_e32 v130, v131, v130
	v_add_f32_e32 v131, v39, v55
	v_exp_f32_e32 v43, v43
	v_exp_f32_e32 v59, v59
	v_add_f32_e32 v130, v131, v130
	v_add_f32_e32 v131, v40, v56
	v_exp_f32_e32 v44, v44
	v_exp_f32_e32 v60, v60
	v_add_f32_e32 v130, v131, v130
	v_add_f32_e32 v131, v41, v57
	v_exp_f32_e32 v45, v45
	v_exp_f32_e32 v61, v61
	v_add_f32_e32 v130, v131, v130
	v_add_f32_e32 v131, v42, v58
	v_add_f32_e32 v130, v131, v130
	v_add_f32_e32 v131, v43, v59
	v_add_f32_e32 v130, v131, v130
	v_add_f32_e32 v131, v44, v60
	v_add_f32_e32 v130, v131, v130
	v_add_f32_e32 v131, v45, v61
	v_add_f32_e32 v130, v131, v130
	v_exp_f32_e32 v131, v46
	v_exp_f32_e32 v62, v62
	v_cvt_pk_bf16_f32 v42, v42, v43
	v_cvt_pk_bf16_f32 v43, v44, v45
	v_add_f32_e32 v46, v131, v62
	v_add_f32_e32 v46, v46, v130
	v_exp_f32_e32 v130, v47
	v_exp_f32_e32 v63, v63
	v_cvt_pk_bf16_f32 v44, v131, v130
	v_add_f32_e32 v47, v130, v63
	v_add_f32_e32 v46, v47, v46
	v_exp_f32_e32 v132, v48
	v_exp_f32_e32 v64, v64
	v_cvt_pk_bf16_f32 v48, v38, v39
	v_cvt_pk_bf16_f32 v38, v50, v51
	v_cvt_pk_bf16_f32 v39, v52, v53
	v_add_f32_e32 v47, v132, v64
	v_add_f32_e32 v46, v47, v46
	v_exp_f32_e32 v133, v49
	v_exp_f32_e32 v65, v65
	v_cvt_pk_bf16_f32 v49, v40, v41
	v_cvt_pk_bf16_f32 v40, v54, v55
	v_cvt_pk_bf16_f32 v41, v56, v57
	v_add_f32_e32 v47, v133, v65
	v_add_f32_e32 v134, v47, v46
	v_cvt_pk_bf16_f32 v46, v34, v35
	v_cvt_pk_bf16_f32 v34, v58, v59
	v_cvt_pk_bf16_f32 v47, v36, v37
	v_cvt_pk_bf16_f32 v45, v132, v133
	v_cvt_pk_bf16_f32 v35, v60, v61
	s_waitcnt lgkmcnt(0)
	v_mfma_f32_32x32x16_bf16 v[2:17], v[136:139], v[46:49], v[2:17]
	v_cvt_pk_bf16_f32 v36, v62, v63
	v_cvt_pk_bf16_f32 v37, v64, v65
	v_fmac_f32_e32 v134, v128, v120
	v_mov_b32_e32 v128, v134
	v_mfma_f32_32x32x16_bf16 v[18:33], v[140:143], v[46:49], v[18:33]
	v_mfma_f32_32x32x16_bf16 v[2:17], v[144:147], v[42:45], v[2:17]
	v_mfma_f32_32x32x16_bf16 v[18:33], v[148:151], v[42:45], v[18:33]
	v_mfma_f32_32x32x16_bf16 v[2:17], v[152:155], v[38:41], v[2:17]
	v_mfma_f32_32x32x16_bf16 v[18:33], v[156:159], v[38:41], v[18:33]
	v_mfma_f32_32x32x16_bf16 v[2:17], v[160:163], v[34:37], v[2:17]
	v_mfma_f32_32x32x16_bf16 v[18:33], v[164:167], v[34:37], v[18:33]
	s_cmp_ge_u32 s44, s38
	s_cbranch_scc0 .LBB0_1185
	s_branch .LBB0_1188
